# dequeue: per-wave 64-entry order-table window (loaded at dispatch) supplies the next entry via v_readlane instead of a dependent global load; fallback to load on miss
# speedup vs baseline: 1.0064x; 1.0064x over previous
; DI void attn_phase(const Params& P, char* shm) {
;     ...
;     for (unsigned k = 0; k < 8; ++k) {
;         const unsigned q = (xcd + k) & 7u; unsigned* cnt = P.counter + 16 * q;
;         for (;;) {
;             if (tid == 0) su[0] = atomicAdd(cnt, 1u);
.LBB0_316:
	v_writelane_b32 v255, 0, 61
	s_nop 0
	s_mov_b32 s0, 0x40000000
	v_writelane_b32 v255, s0, 62
	s_nop 0
	v_readlane_b32 s0, v255, 29
	s_add_i32 s0, s1, s0
	v_writelane_b32 v255, s1, 45
	s_and_b32 s0, s0, 7
	s_lshl_b32 s1, s0, 6
	v_readlane_b32 s2, v255, 25
	s_add_u32 s42, s2, s1
	v_readlane_b32 s1, v255, 26
	s_mul_i32 s41, s0, 0x180
	s_addc_u32 s43, s1, 0
	v_writelane_b32 v255, s41, 46
	v_writelane_b32 v255, s42, 47
	s_nop 1
	v_writelane_b32 v255, s43, 48
	s_branch .LBB0_320

; template <int KIND> DI void attn_unit(const Params& P, int b, int h, int qb, char* shm, float lam, bool dry = false) {
;     ...
;     else { qrow0 = qb * 256 + 32 * wid; qoff = 1024 + h * 64; T_lo = 0; T_hi = 4 * qb + 3; wt_lo = 0; wt_hi = 4 * qb + (wid >> 1); }
;     const int kvoff = (KIND == 0) ? h * 128 : qoff;
;     const unsigned lds0 = (unsigned)(uintptr_t)shm;
;     const lds_cptr shm3 = (lds_cptr)shm;
;     const int hk = kvoff >> 6, vb0 = kvoff >> 5;
;     const bf16_t* ksrc = P.Kp + ((size_t)(b * 24 + hk) * 256) * 4096 + wid * 512 + lane * 8;
;     const bf16_t* vsrc0 = P.Vp + ((size_t)(b * 48 + vb0 + (wid >> 2)) * 256) * 2048 + (wid & 3) * 512 + lane * 8;
;     const bf16_t* kxsrc = P.KX + ((size_t)(b * 8 + h) * SEQ + lane) * 8;
;     ...
;     float cb = 0.f;
;     if (KIND == 0) { cb = P.t5[15 * 4 + h] * LOG2E;
;         for (int i = tid; i < 2175; i += 512) { const int rel = i - 2111; const int n = rel < 0 ? -rel : rel;
;             int lg = 36 - __builtin_clz((unsigned)(n | 1)); lg = lg > 15 ? 15 : lg; int idx = n < 8 ? n : lg; idx += rel > 0 ? 16 : 0;
;             *(LAS float*)(shm3 + OFF_TAB + i * 4) = P.t5[idx * 4 + h] * LOG2E - cb; } }
;     if (KIND == 1) { cb = P.relb[h] * LOG2E;
;         if (tid < 255) { int idx = tid - 191; idx = idx < -128 ? -128 : idx; *(LAS float*)(shm3 + OFF_TAB + tid * 4) = P.relb[(idx + 128) * 8 + h] * LOG2E - cb; } }
;     const int NT = T_hi - T_lo + 1;
;     ...
;     ATT_DMA(ATT_TILE(0), 0);
;     if (NT > 1) ATT_DMA(ATT_TILE(1), SLOT);
; DI void attn_phase(const Params& P, char* shm) {
;     ...
;             if (tid == 0) su[0] = atomicAdd(cnt, 1u);
;             ATT_WAIT_BAR();
;             const unsigned ui = su[0];
;             ATT_WAIT_BAR();
;             if (ui >= 384u) break;
;             const unsigned e = P.order[q * 384 + ui]; const int kind = e >> 28, b = (e >> 24) & 15, h = (e >> 16) & 255, qb = e & 0xffff;
;     ...
;             { const int reps = (kind == 0) ? PROBE_REP_A : (kind == 2 ? PROBE_REP_C : 1);
;               for (int rep = 1; rep < reps; ++rep) { if (kind == 0) attn_unit<0>(P, b, h, qb, shm, lam, P.lam_init > -1.0f); else attn_unit<2>(P, b, h, qb, shm, lam, P.lam_init > -1.0f); ATT_WAIT_BAR(); } }
;     ...
;             if (kind == 0) attn_unit<0>(P, b, h, qb, shm, lam);
;             else if (kind == 1) attn_unit<1>(P, b, h, qb, shm, lam);
;             else attn_unit<2>(P, b, h, qb, shm, lam);
.LBB0_324:
	s_or_b64 exec, exec, s[0:1]
	v_writelane_b32 v255, 0, 61
	s_waitcnt lgkmcnt(0)
	s_barrier
	v_mov_b32_e32 v0, s87
	ds_read_b32 v0, v0
	s_waitcnt lgkmcnt(0)
	s_barrier
	s_movk_i32 s0, 0x17f
	s_waitcnt lgkmcnt(0)
	v_cmp_lt_u32_e32 vcc, s0, v0
	s_mov_b64 s[0:1], -1
	s_cbranch_vccnz .LBB0_319
	v_add_u32_e32 v0, s41, v0
	v_mbcnt_lo_u32_b32 v1, -1, 0
	v_mbcnt_hi_u32_b32 v1, -1, v1
	v_add_u32_e32 v1, v1, v0
	v_lshlrev_b32_e32 v1, 2, v1
	v_readfirstlane_b32 s2, v0
	v_readlane_b32 s0, v255, 62
	s_sub_u32 s0, s2, s0
	s_add_u32 s2, s2, 1
	s_cmp_lt_u32 s0, 64
	s_cbranch_scc0 .Ldq_miss
	v_readlane_b32 s1, v213, s0
	v_writelane_b32 v255, s2, 62
	global_load_dword v213, v1, s[22:23] offset:4
	s_nop 0
	v_mov_b32_e32 v166, s1
	s_brev_b32 s1, -16
	s_branch .Ldq_dec
.Ldq_miss:
	v_writelane_b32 v255, s2, 62
	global_load_dword v213, v1, s[22:23] offset:4
	v_mov_b32_e32 v1, v2
	v_lshlrev_b64 v[0:1], 2, v[0:1]
	v_lshl_add_u64 v[0:1], s[22:23], 0, v[0:1]
	global_load_dword v166, v[0:1], off
	s_brev_b32 s1, -16
	s_waitcnt vmcnt(0)
.Ldq_dec:
	v_readfirstlane_b32 s0, v166
	v_cmp_lt_u32_e32 vcc, s1, v166
	s_bfe_u32 s2, s0, 0x40018
	s_bfe_u32 s28, s0, 0x80010
	s_and_b32 s3, s0, 0xffff
	s_mov_b64 s[0:1], -1
	s_cbranch_vccz .LBB0_377
	s_brev_b32 s0, -8
	v_cmp_lt_u32_e32 vcc, s0, v166
	s_lshl_b32 s14, s2, 14
	s_lshl_b32 s16, s3, 8
	s_lshl_b32 s15, s28, 6
	s_lshl_b32 s33, s3, 2
	s_mov_b64 s[0:1], -1
	s_mul_i32 s10, s2, 24
	s_cbranch_vccz .LBB0_365
	s_add_i32 s0, s15, 0x400
	v_mov_b32_e32 v53, v236
	s_lshr_b32 s1, s0, 6
	s_add_i32 s1, s1, s10
	v_readfirstlane_b32 s9, v53
	s_ashr_i32 s8, s9, 6
	s_or_b32 s7, s33, 3
	s_lshr_b32 s4, s0, 5
	s_lshl_b32 s0, s1, 21
	s_add_u32 s5, s24, s0
	s_addc_u32 s6, s25, 0
	s_lshl_b32 s0, s8, 9
	s_ashr_i32 s1, s0, 31
	s_lshl_b64 s[0:1], s[0:1], 1
	v_and_b32_e32 v52, 63, v53
	s_add_u32 s0, s5, s0
	s_addc_u32 s1, s6, s1
	v_lshlrev_b32_e32 v0, 4, v52
	v_mov_b32_e32 v1, v2
	v_lshl_add_u64 v[156:157], s[0:1], 0, v[0:1]
	s_mul_i32 s0, s2, 48
	s_add_i32 s0, s4, s0
	s_ashr_i32 s1, s9, 8
	s_add_i32 s0, s0, s1
	s_ashr_i32 s1, s0, 31
	s_lshl_b64 s[0:1], s[0:1], 20
	s_add_u32 s0, s26, s0
	s_addc_u32 s1, s27, s1
	s_lshl_b32 s41, s8, 10
	s_and_b32 s4, s41, 0xc00
	s_add_u32 s0, s0, s4
	s_addc_u32 s1, s1, 0
	s_lshl_b32 s11, s2, 3
	s_add_i32 s11, s11, s28
	s_lshl_b32 s6, s11, 14
	v_lshl_add_u64 v[158:159], s[0:1], 0, v[0:1]
	v_or_b32_e32 v0, s6, v52
	v_readlane_b32 s0, v255, 19
	s_lshl_b32 s20, s7, 13
	v_lshlrev_b32_e32 v0, 4, v0
	v_readlane_b32 s1, v255, 20
	s_cmp_lg_u32 0, -1
	s_nop 0
	v_lshl_add_u64 v[160:161], s[0:1], 0, v[0:1]
	s_cselect_b32 s0, 0, 0
	s_add_i32 s0, s41, s0
	v_lshl_add_u64 v[0:1], v[156:157], 0, s[20:21]
	s_mov_b32 s1, m0
	s_mov_b32 m0, s0
	s_nop 0
	global_load_lds_dwordx4 v[0:1], off
	s_mov_b32 m0, s1
	s_lshl_b32 s20, s7, 12
	s_addk_i32 s0, 0x4000
	s_cmp_lt_u32 s9, 64
	v_lshl_add_u64 v[0:1], v[158:159], 0, s[20:21]
	s_mov_b32 s1, m0
	s_mov_b32 m0, s0
	s_nop 0
	global_load_lds_dwordx4 v[0:1], off
	s_mov_b32 m0, s1
	s_cselect_b64 s[4:5], -1, 0
	s_cmp_gt_u32 s9, 63
	s_cselect_b64 s[0:1], -1, 0
	s_and_b64 vcc, exec, s[0:1]
	s_cbranch_vccnz .LBB0_329
	s_lshl_b32 s20, s7, 10
	s_cmp_lg_u32 0, -1
	s_cselect_b32 s7, 0, 0
	v_lshl_add_u64 v[0:1], v[160:161], 0, s[20:21]
	s_add_i32 s7, s7, 0x8000
	s_mov_b32 s10, m0
	s_mov_b32 m0, s7
	s_nop 0
	global_load_lds_dwordx4 v[0:1], off
	s_mov_b32 m0, s10
